# v54 + prologue wconv loop de-serialisation: next-tile prefetch loads no longer waited right after issue; mask saved in s[100:101], select + vmcnt(0) moved to just before the tile store
# baseline (speedup 1.0000x reference)
; #define LAS __attribute__((address_space(3)))
; __device__ __forceinline__ unsigned pk2(float lo, float hi) { f32x2_t v = {lo, hi}; bf16x2_t b = __builtin_convertvector(v, bf16x2_t); return __builtin_bit_cast(unsigned, b); }
; __device__ __forceinline__ void wc_load(const WcItem& w, int tid, float (&v)[8]) {
;     const int nn = tid & 63, kk = tid >> 6, pcol = w.n0 + nn;
;     const int col = w.mode == 0 ? win_col(pcol) : (w.mode == 2 ? wf1_col(pcol) : pcol);
;     const float* src = w.W + (size_t)(w.k0 + kk) * w.Nlog + (col >= 0 ? col : 0);
; #pragma unroll
;     for (int i = 0; i < 8; ++i) { const float x = src[(size_t)(8 * i) * w.Nlog]; v[i] = col >= 0 ? x : 0.f; }
; }
; __device__ __forceinline__ void wconv_phase(const Params& p, int l, int which, LAS unsigned char* lds) {
;     ...
;     for (;;) {
;         const int nxt = it + gridDim.x; const bool has = nxt < tot;
;         WcItem nw = cur; float vn[8];
;         if (has) { nw = wc_decode(p, l, which, nxt); wc_load(nw, tid, vn); }
;         { const int nn = tid & 63, kk = tid >> 6;
; #pragma unroll
;           for (int i = 0; i < 8; ++i) tl[(kk + 8 * i) * 65 + nn] = v[i]; }
;         __syncthreads();
;         { const int n = tid >> 3, c = tid & 7; const LAS float* s = tl + (8 * c) * 65 + n;
;           u32x4 o; o.x = pk2(s[0], s[65]); o.y = pk2(s[2 * 65], s[3 * 65]); o.z = pk2(s[4 * 65], s[5 * 65]); o.w = pk2(s[6 * 65], s[7 * 65]);
;           *(u32x4*)(cur.Wt + (size_t)(cur.n0 + n) * cur.K + cur.k0 + 8 * c) = o; }
;         __syncthreads();
;         if (!has) break;
;         it = nxt; cur = nw;
; #pragma unroll
;         for (int i = 0; i < 8; ++i) v[i] = vn[i];
;     }
.LBB0_63:
	s_lshl_b32 s0, s33, 6
	v_add_u32_e32 v19, s0, v4
	v_ashrrev_i32_e32 v21, 31, v19
	v_mul_lo_u32 v21, s24, v21
	v_mul_lo_u32 v24, s25, v19
	v_mad_u64_u32 v[22:23], s[26:27], s24, v19, 0
	v_cmp_lt_i32_e32 vcc, -1, v20
	s_mov_b64 s[100:101], vcc
	v_add3_u32 v23, v23, v21, v24
	v_lshl_add_u64 v[22:23], v[22:23], 2, s[22:23]
	v_cndmask_b32_e32 v20, 0, v20, vcc
	v_ashrrev_i32_e32 v21, 31, v20
	v_lshl_add_u64 v[20:21], v[20:21], 2, v[22:23]
	s_lshl_b64 s[22:23], s[24:25], 5
	v_lshl_add_u64 v[22:23], v[20:21], 0, s[22:23]
	v_lshl_add_u64 v[24:25], v[22:23], 0, s[22:23]
	v_lshl_add_u64 v[26:27], v[24:25], 0, s[22:23]
	v_lshl_add_u64 v[28:29], v[26:27], 0, s[22:23]
	v_lshl_add_u64 v[30:31], v[28:29], 0, s[22:23]
	v_lshl_add_u64 v[32:33], v[30:31], 0, s[22:23]
	v_lshl_add_u64 v[34:35], v[32:33], 0, s[22:23]
	global_load_dword v19, v[20:21], off
	s_nop 0
	global_load_dword v20, v[22:23], off
	global_load_dword v21, v[24:25], off
	s_nop 0
	global_load_dword v22, v[26:27], off
	global_load_dword v23, v[28:29], off
	global_load_dword v24, v[30:31], off
	global_load_dword v25, v[32:33], off
	s_nop 0
	global_load_dword v26, v[34:35], off
.LBB0_64:
	ds_write_b32 v9, v11
	ds_write_b32 v9, v12 offset:2080
	ds_write_b32 v9, v13 offset:4160
	ds_write_b32 v9, v14 offset:6240
	ds_write_b32 v9, v15 offset:8320
	ds_write_b32 v9, v16 offset:10400
	ds_write_b32 v9, v17 offset:12480
	ds_write_b32 v9, v18 offset:14560
	s_waitcnt lgkmcnt(0)
	s_barrier
	ds_read2_b32 v[12:13], v10 offset1:65
	ds_read2_b32 v[14:15], v10 offset0:130 offset1:195
	v_add_u32_e32 v11, 0x400, v10
	ds_read2_b32 v[16:17], v11 offset0:4 offset1:69
	ds_read2_b32 v[28:29], v11 offset0:134 offset1:199
	v_add_u32_e32 v11, s28, v5
	s_waitcnt lgkmcnt(3)
	v_cvt_pk_bf16_f32 v12, v12, v13
	s_waitcnt lgkmcnt(2)
	v_cvt_pk_bf16_f32 v13, v14, v15
	s_waitcnt lgkmcnt(1)
	v_cvt_pk_bf16_f32 v14, v16, v17
	v_mad_u64_u32 v[16:17], s[22:23], s3, v11, 0
	v_ashrrev_i32_e32 v27, 31, v11
	v_mov_b32_e32 v18, v17
	s_waitcnt lgkmcnt(0)
	v_cvt_pk_bf16_f32 v15, v28, v29
	v_mad_u64_u32 v[28:29], s[22:23], s3, v27, v[18:19]
	v_mov_b32_e32 v17, v28
	v_lshl_add_u64 v[16:17], v[16:17], 1, s[6:7]
	s_ashr_i32 s5, s4, 31
	v_lshl_add_u64 v[16:17], s[4:5], 1, v[16:17]
	v_lshl_add_u64 v[16:17], v[16:17], 0, v[2:3]
	s_waitcnt vmcnt(0)
	v_cndmask_b32_e64 v19, 0, v19, s[100:101]
	v_cndmask_b32_e64 v20, 0, v20, s[100:101]
	v_cndmask_b32_e64 v21, 0, v21, s[100:101]
	v_cndmask_b32_e64 v22, 0, v22, s[100:101]
	v_cndmask_b32_e64 v23, 0, v23, s[100:101]
	v_cndmask_b32_e64 v24, 0, v24, s[100:101]
	v_cndmask_b32_e64 v25, 0, v25, s[100:101]
	v_cndmask_b32_e64 v26, 0, v26, s[100:101]
	global_store_dwordx4 v[16:17], v[12:15], off
	s_andn2_b64 vcc, exec, s[18:19]
	s_mov_b32 s28, s31
	s_mov_b32 s4, s0
	s_mov_b32 s3, s30
	s_mov_b64 s[6:7], s[20:21]
	v_mov_b32_e32 v11, v19
	v_mov_b32_e32 v12, v20
	v_mov_b32_e32 v13, v21
	v_mov_b32_e32 v14, v22
	v_mov_b32_e32 v15, v23
	v_mov_b32_e32 v16, v24
	v_mov_b32_e32 v17, v25
	v_mov_b32_e32 v18, v26
	s_barrier
	s_cbranch_vccz .LBB0_88
